# QK RMSNorm fused into phase-B epilogue for q/k tiles (f32 accumulators), separate qknorm pass removed
# speedup vs baseline: 1.0052x; 1.0052x over previous
; __device__ __forceinline__ int opaque_tid(int wid) { int wv_ = wid; asm volatile("" : "+v"(wv_)); wv_ = __builtin_amdgcn_readfirstlane(wv_); unsigned ones = ~0u; asm volatile("" : "+s"(ones)); int t = (wv_ << 6) | (int)__builtin_amdgcn_mbcnt_hi(ones, __builtin_amdgcn_mbcnt_lo(ones, 0u)); asm volatile("" : "+v"(t)); return t; }
; __device__ void ph_qknorm(bf16_t* Z, const float* qg, const float* kg, const int WID) {
;     const int tid = opaque_tid(WID), lane = tid & 63, gw = blockIdx.x * 8 + __builtin_amdgcn_readfirstlane(tid >> 6);
;     f32x4 qgv[4], kgv[4];
; #pragma unroll
;     for (int e = 0; e < 4; ++e) { qgv[e] = *(const f32x4*)(qg + (lane & 7) * 16 + e * 4); kgv[e] = *(const f32x4*)(kg + (lane & 7) * 16 + e * 4); }
;     for (int it0 = gw * 4; it0 < 2 * CH; it0 += NWAVES_TOTAL * 4) {
.LBB0_1009:
	v_mov_b32_e32 v1, s82
	s_barrier
	s_mov_b32 s1, -1
	v_readfirstlane_b32 s0, v1
	s_mov_b64 s[20:21], 0x1000
	v_mbcnt_lo_u32_b32 v1, s1, 0
	v_mbcnt_hi_u32_b32 v1, s1, v1
	v_lshl_or_b32 v1, s0, 6, v1
	v_readlane_b32 s1, v254, 46
	v_readfirstlane_b32 s0, v1
	s_ashr_i32 s0, s0, 4
	s_and_b32 s0, s0, -4
	s_add_i32 s2, s0, s1
	s_cmpk_gt_i32 s2, 0x7fff
	s_branch .LBB0_1012
	v_readlane_b32 s0, v255, 4
	v_readlane_b32 s1, v255, 5
	s_and_b64 s[0:1], s[0:1], exec
	v_readlane_b32 s4, v254, 8
	s_cselect_b32 s3, 0x200, 0
	v_readlane_b32 s10, v254, 14
	v_readlane_b32 s11, v254, 15
	s_add_u32 s0, s10, s3
	v_readlane_b32 s12, v254, 16
	s_addc_u32 s1, s11, 0
	v_lshlrev_b32_e32 v2, 6, v1
	v_readlane_b32 s5, v254, 9
	v_readlane_b32 s13, v254, 17
	s_add_u32 s4, s12, s3
	v_and_b32_e32 v30, 0x1c0, v2
	s_addc_u32 s5, s13, 0
	global_load_dwordx4 v[2:5], v30, s[0:1] offset:48
	global_load_dwordx4 v[6:9], v30, s[0:1] offset:32
	global_load_dwordx4 v[10:13], v30, s[0:1] offset:16
	global_load_dwordx4 v[14:17], v30, s[0:1]
	global_load_dwordx4 v[18:21], v30, s[4:5] offset:48
	global_load_dwordx4 v[22:25], v30, s[4:5] offset:32
	global_load_dwordx4 v[26:29], v30, s[4:5] offset:16
	s_nop 0
	global_load_dwordx4 v[30:33], v30, s[4:5]
	v_lshlrev_b32_e32 v1, 4, v1
	v_and_b32_e32 v35, 64, v248
	v_and_b32_e32 v34, 0x3f0, v1
	v_xor_b32_e32 v1, 1, v248
	v_add_u32_e32 v35, 64, v35
	v_cmp_lt_i32_e32 vcc, v1, v35
	v_xor_b32_e32 v36, 2, v248
	v_lshlrev_b32_e32 v34, 1, v34
	v_cndmask_b32_e32 v1, v248, v1, vcc
	v_cmp_lt_i32_e32 vcc, v36, v35
	v_lshlrev_b32_e32 v1, 2, v1
	v_readlane_b32 s6, v254, 10
	v_cndmask_b32_e32 v36, v248, v36, vcc
	v_lshlrev_b32_e32 v40, 2, v36
	v_xor_b32_e32 v36, 4, v248
	v_cmp_lt_i32_e32 vcc, v36, v35
	v_readlane_b32 s7, v254, 11
	v_readlane_b32 s8, v254, 12
	v_cndmask_b32_e32 v35, v248, v36, vcc
	v_lshlrev_b32_e32 v41, 2, v35
	v_readlane_b32 s9, v254, 13
	v_readlane_b32 s14, v254, 18
	v_readlane_b32 s15, v254, 19
	v_readlane_b32 s16, v254, 20
	v_readlane_b32 s17, v254, 21
	v_readlane_b32 s18, v254, 22
	v_readlane_b32 s19, v254, 23

;     __device__ __forceinline__ void operator()(const AccT& acc, const Unit& u, int wr, int wc, int fr, int fq) const {
;     ...
;         if (u.aux == 0) {
;             const bool gate = u.pn >= 12;
;             float rsv[2][4]; f32x4 bb0[2], bb1[2];
; #pragma unroll
;             for (int ai = 0; ai < 2; ++ai)
; #pragma unroll
;                 for (int m = 0; m < 4; ++m) rsv[ai][m] = SS[row0 + ai * 128 + m * 16];
; #pragma unroll
;             for (int bj = 0; bj < 2; ++bj) { bb0[bj] = (f32x4){0.f, 0.f, 0.f, 0.f}; bb1[bj] = bb0[bj];
;                 if (gate) { bb0[bj] = *(const f32x4*)(bg + col0 + bj * 128 - ZG); bb1[bj] = *(const f32x4*)(bg + col0 + bj * 128 - ZG + 4); } }
.LBB0_1107:
	s_mov_b32 s97, 0x132000
	s_cbranch_execz .LBB0_1033
	s_cmp_lt_i32 s16, 4
	s_cbranch_scc1 .Lqk_no
	s_cmp_lt_i32 s16, 12
	s_cbranch_scc1 .Lqk_epi
.Lqk_no:
	v_or_b32_e32 v168, 16, v160
	v_or_b32_e32 v166, 32, v160
	v_or_b32_e32 v164, 48, v160
	v_lshl_add_u64 v[130:131], v[160:161], 2, s[76:77]
	v_ashrrev_i32_e32 v169, 31, v168
	v_ashrrev_i32_e32 v167, 31, v166
	v_ashrrev_i32_e32 v165, 31, v164
	v_lshl_add_u64 v[132:133], v[168:169], 2, s[76:77]
	v_lshl_add_u64 v[134:135], v[166:167], 2, s[76:77]
	v_lshl_add_u64 v[136:137], v[164:165], 2, s[76:77]
	global_load_dword v173, v[130:131], off
	global_load_dword v172, v[132:133], off
	global_load_dword v171, v[134:135], off
	global_load_dword v170, v[136:137], off
	global_load_dword v169, v[130:131], off offset:512
	global_load_dword v167, v[130:131], off offset:576
	global_load_dword v165, v[130:131], off offset:640
	global_load_dword v161, v[130:131], off offset:704
	s_cmp_gt_i32 s16, 11
	v_mov_b32_e32 v130, v158
	v_mov_b32_e32 v131, v0
	s_cselect_b64 s[18:19], -1, 0
	s_cmp_lt_i32 s16, 12
	v_lshl_add_u64 v[162:163], v[130:131], 2, s[66:67]
	v_mov_b32_e32 v130, 0
	v_mov_b32_e32 v138, 0
	v_mov_b32_e32 v139, 0
	v_mov_b32_e32 v140, 0
	v_mov_b32_e32 v141, 0
	v_mov_b32_e32 v142, 0
	v_mov_b32_e32 v143, 0
	v_mov_b32_e32 v144, 0
	v_mov_b32_e32 v145, 0
	s_cbranch_scc1 .LBB0_1110
	s_movk_i32 s0, 0xd000
	v_add_co_u32_e32 v134, vcc, 0xffffd000, v162
	s_mov_b32 s1, -1
	s_nop 0
	v_addc_co_u32_e32 v135, vcc, -1, v163, vcc
	v_lshl_add_u64 v[132:133], v[162:163], 0, s[0:1]
	global_load_dwordx4 v[142:145], v[134:135], off
	global_load_dwordx4 v[138:141], v[132:133], off offset:16

; __device__ __forceinline__ float rstd_of(float ss) { return rsqrtf(ss * (1.0f / DM) + EPS); }
;     __device__ __forceinline__ void operator()(const AccT& acc, const Unit& u, int wr, int wc, int fr, int fq) const {
;     ...
;                 for (int m = 0; m < 4; ++m) rsv[ai][m] = SS[row0 + ai * 128 + m * 16];
; #pragma unroll
;             for (int bj = 0; bj < 2; ++bj) { bb0[bj] = (f32x4){0.f, 0.f, 0.f, 0.f}; bb1[bj] = bb0[bj];
;                 if (gate) { bb0[bj] = *(const f32x4*)(bg + col0 + bj * 128 - ZG); bb1[bj] = *(const f32x4*)(bg + col0 + bj * 128 - ZG + 4); } }
; #pragma unroll
;             for (int bj = 0; bj < 2; ++bj) {
;                 const f32x4 b0 = bb0[bj], b1 = bb1[bj];
; #pragma unroll
;                 for (int ai = 0; ai < 2; ++ai)
; #pragma unroll
;                     for (int m = 0; m < 4; ++m) {
;                         const float rs = rstd_of(rsv[ai][m]);
;                         f32x4 v0 = acc[ai][bj][m][0] * rs, v1 = acc[ai][bj][m][1] * rs;
; __device__ void ph_qknorm(bf16_t* Z, const float* qg, const float* kg, const int WID) {
;     ...
;             float ss = 0.f;
; #pragma unroll
;             for (int j = 0; j < 4; ++j) ss += a0[j] * a0[j] + a1[j] * a1[j] + a2[j] * a2[j] + a3[j] * a3[j];
.Lqk_epi:
	v_lshlrev_b32_e32 v162, 2, v160
	global_load_dword v130, v162, s[76:77] offset:0
	global_load_dword v131, v162, s[76:77] offset:64
	global_load_dword v132, v162, s[76:77] offset:128
	global_load_dword v133, v162, s[76:77] offset:192
	global_load_dword v134, v162, s[76:77] offset:512
	global_load_dword v135, v162, s[76:77] offset:576
	global_load_dword v136, v162, s[76:77] offset:640
	global_load_dword v137, v162, s[76:77] offset:704
	s_cmp_gt_i32 s16, 7
	s_cselect_b32 s11, 1.0, 0x3db504f3
	v_readlane_b32 s0, v254, 14
	v_readlane_b32 s1, v254, 15
	s_cbranch_scc0 .Lqk_g
	v_readlane_b32 s0, v254, 16
	v_readlane_b32 s1, v254, 17
.Lqk_g:
	v_readlane_b32 s18, v255, 4
	v_readlane_b32 s19, v255, 5
	v_lshlrev_b32_e32 v161, 2, v175
	v_xor_b32_e32 v164, 16, v248
	v_xor_b32_e32 v165, 32, v248
	s_and_b64 s[18:19], s[18:19], exec
	s_cselect_b32 s18, 0x200, 0
	s_add_u32 s0, s0, s18
	s_addc_u32 s1, s1, 0
	v_lshlrev_b32_e32 v164, 2, v164
	v_lshlrev_b32_e32 v165, 2, v165
	v_lshrrev_b32_e32 v166, 5, v175
	v_and_b32_e32 v166, 3, v166
	v_lshlrev_b32_e32 v167, 5, v1
	global_load_dwordx4 v[138:141], v161, s[0:1]
	global_load_dwordx4 v[142:145], v161, s[0:1] offset:16
	v_add_u32_e32 v167, 0x20000, v167
	v_lshl_add_u32 v166, v166, 2, v167
	v_mul_u32_u24_e32 v163, 0x4800, v160
	v_lshl_add_u32 v163, v158, 1, v163
	s_waitcnt vmcnt(2)
	v_fmamk_f32 v130, v130, 0x3a000000, v251
	v_fmamk_f32 v131, v131, 0x3a000000, v251
	v_fmamk_f32 v132, v132, 0x3a000000, v251
	v_fmamk_f32 v133, v133, 0x3a000000, v251
	v_fmamk_f32 v134, v134, 0x3a000000, v251
	v_fmamk_f32 v135, v135, 0x3a000000, v251
	v_fmamk_f32 v136, v136, 0x3a000000, v251
	v_fmamk_f32 v137, v137, 0x3a000000, v251
	v_rsq_f32_e32 v130, v130
	v_rsq_f32_e32 v131, v131
	v_rsq_f32_e32 v132, v132
	v_rsq_f32_e32 v133, v133
	v_rsq_f32_e32 v134, v134
	v_rsq_f32_e32 v135, v135
	v_rsq_f32_e32 v136, v136
	v_rsq_f32_e32 v137, v137
	v_mul_f32_e32 v126, v130, v126
	v_mul_f32_e32 v127, v130, v127
	v_mul_f32_e32 v128, v130, v128
	v_mul_f32_e32 v129, v130, v129
	v_mul_f32_e32 v122, v130, v122
	v_mul_f32_e32 v123, v130, v123
	v_mul_f32_e32 v124, v130, v124
	v_mul_f32_e32 v125, v130, v125
	v_mul_f32_e32 v178, v126, v126
	v_fmac_f32_e32 v178, v127, v127
	v_fmac_f32_e32 v178, v128, v128
	v_fmac_f32_e32 v178, v129, v129
	v_fmac_f32_e32 v178, v122, v122
	v_fmac_f32_e32 v178, v123, v123
	v_fmac_f32_e32 v178, v124, v124
	v_fmac_f32_e32 v178, v125, v125
	v_mul_f32_e32 v62, v130, v62
	v_mul_f32_e32 v63, v130, v63
	v_mul_f32_e32 v64, v130, v64
	v_mul_f32_e32 v65, v130, v65
	v_mul_f32_e32 v58, v130, v58
	v_mul_f32_e32 v59, v130, v59
	v_mul_f32_e32 v60, v130, v60
	v_mul_f32_e32 v61, v130, v61
	v_mul_f32_e32 v179, v62, v62
	v_fmac_f32_e32 v179, v63, v63
	v_fmac_f32_e32 v179, v64, v64
	v_fmac_f32_e32 v179, v65, v65
	v_fmac_f32_e32 v179, v58, v58
	v_fmac_f32_e32 v179, v59, v59
	v_fmac_f32_e32 v179, v60, v60
	v_fmac_f32_e32 v179, v61, v61
	v_mul_f32_e32 v118, v131, v118
	v_mul_f32_e32 v119, v131, v119
	v_mul_f32_e32 v120, v131, v120
	v_mul_f32_e32 v121, v131, v121
	v_mul_f32_e32 v114, v131, v114
	v_mul_f32_e32 v115, v131, v115
	v_mul_f32_e32 v116, v131, v116
	v_mul_f32_e32 v117, v131, v117
	v_mul_f32_e32 v180, v118, v118
	v_fmac_f32_e32 v180, v119, v119
	v_fmac_f32_e32 v180, v120, v120
	v_fmac_f32_e32 v180, v121, v121
	v_fmac_f32_e32 v180, v114, v114
	v_fmac_f32_e32 v180, v115, v115
	v_fmac_f32_e32 v180, v116, v116
	v_fmac_f32_e32 v180, v117, v117
	v_mul_f32_e32 v54, v131, v54
	v_mul_f32_e32 v55, v131, v55
	v_mul_f32_e32 v56, v131, v56
	v_mul_f32_e32 v57, v131, v57
	v_mul_f32_e32 v50, v131, v50
	v_mul_f32_e32 v51, v131, v51
	v_mul_f32_e32 v52, v131, v52
	v_mul_f32_e32 v53, v131, v53
	v_mul_f32_e32 v181, v54, v54
	v_fmac_f32_e32 v181, v55, v55
	v_fmac_f32_e32 v181, v56, v56
	v_fmac_f32_e32 v181, v57, v57
	v_fmac_f32_e32 v181, v50, v50
	v_fmac_f32_e32 v181, v51, v51
	v_fmac_f32_e32 v181, v52, v52
	v_fmac_f32_e32 v181, v53, v53
	v_mul_f32_e32 v110, v132, v110
	v_mul_f32_e32 v111, v132, v111
	v_mul_f32_e32 v112, v132, v112
	v_mul_f32_e32 v113, v132, v113
	v_mul_f32_e32 v106, v132, v106
	v_mul_f32_e32 v107, v132, v107
	v_mul_f32_e32 v108, v132, v108
	v_mul_f32_e32 v109, v132, v109
	v_mul_f32_e32 v182, v110, v110
	v_fmac_f32_e32 v182, v111, v111
	v_fmac_f32_e32 v182, v112, v112
	v_fmac_f32_e32 v182, v113, v113
	v_fmac_f32_e32 v182, v106, v106
	v_fmac_f32_e32 v182, v107, v107
	v_fmac_f32_e32 v182, v108, v108
	v_fmac_f32_e32 v182, v109, v109
	v_mul_f32_e32 v46, v132, v46
	v_mul_f32_e32 v47, v132, v47
	v_mul_f32_e32 v48, v132, v48
	v_mul_f32_e32 v49, v132, v49
	v_mul_f32_e32 v42, v132, v42
	v_mul_f32_e32 v43, v132, v43
	v_mul_f32_e32 v44, v132, v44
	v_mul_f32_e32 v45, v132, v45
	v_mul_f32_e32 v183, v46, v46
	v_fmac_f32_e32 v183, v47, v47
	v_fmac_f32_e32 v183, v48, v48
	v_fmac_f32_e32 v183, v49, v49
	v_fmac_f32_e32 v183, v42, v42
	v_fmac_f32_e32 v183, v43, v43
	v_fmac_f32_e32 v183, v44, v44
	v_fmac_f32_e32 v183, v45, v45
	v_mul_f32_e32 v102, v133, v102
	v_mul_f32_e32 v103, v133, v103
	v_mul_f32_e32 v104, v133, v104
	v_mul_f32_e32 v105, v133, v105
	v_mul_f32_e32 v98, v133, v98
	v_mul_f32_e32 v99, v133, v99
	v_mul_f32_e32 v100, v133, v100
	v_mul_f32_e32 v101, v133, v101
	v_mul_f32_e32 v184, v102, v102
	v_fmac_f32_e32 v184, v103, v103
	v_fmac_f32_e32 v184, v104, v104
	v_fmac_f32_e32 v184, v105, v105
	v_fmac_f32_e32 v184, v98, v98
	v_fmac_f32_e32 v184, v99, v99
	v_fmac_f32_e32 v184, v100, v100
	v_fmac_f32_e32 v184, v101, v101
	v_mul_f32_e32 v38, v133, v38
	v_mul_f32_e32 v39, v133, v39
	v_mul_f32_e32 v40, v133, v40
	v_mul_f32_e32 v41, v133, v41
	v_mul_f32_e32 v34, v133, v34
	v_mul_f32_e32 v35, v133, v35
	v_mul_f32_e32 v36, v133, v36
	v_mul_f32_e32 v37, v133, v37
; __device__ void ph_qknorm(bf16_t* Z, const float* qg, const float* kg, const int WID) {
;     ...
;             float ss = 0.f;
; #pragma unroll
;             for (int j = 0; j < 4; ++j) ss += a0[j] * a0[j] + a1[j] * a1[j] + a2[j] * a2[j] + a3[j] * a3[j];
;             ss += __shfl_xor(ss, 1); ss += __shfl_xor(ss, 2); ss += __shfl_xor(ss, 4);
	v_mul_f32_e32 v185, v38, v38
	v_fmac_f32_e32 v185, v39, v39
	v_fmac_f32_e32 v185, v40, v40
	v_fmac_f32_e32 v185, v41, v41
	v_fmac_f32_e32 v185, v34, v34
	v_fmac_f32_e32 v185, v35, v35
	v_fmac_f32_e32 v185, v36, v36
	v_fmac_f32_e32 v185, v37, v37
	v_mul_f32_e32 v94, v134, v94
	v_mul_f32_e32 v95, v134, v95
	v_mul_f32_e32 v96, v134, v96
	v_mul_f32_e32 v97, v134, v97
	v_mul_f32_e32 v90, v134, v90
	v_mul_f32_e32 v91, v134, v91
	v_mul_f32_e32 v92, v134, v92
	v_mul_f32_e32 v93, v134, v93
	v_mul_f32_e32 v186, v94, v94
	v_fmac_f32_e32 v186, v95, v95
	v_fmac_f32_e32 v186, v96, v96
	v_fmac_f32_e32 v186, v97, v97
	v_fmac_f32_e32 v186, v90, v90
	v_fmac_f32_e32 v186, v91, v91
	v_fmac_f32_e32 v186, v92, v92
	v_fmac_f32_e32 v186, v93, v93
	v_mul_f32_e32 v30, v134, v30
	v_mul_f32_e32 v31, v134, v31
	v_mul_f32_e32 v32, v134, v32
	v_mul_f32_e32 v33, v134, v33
	v_mul_f32_e32 v26, v134, v26
	v_mul_f32_e32 v27, v134, v27
	v_mul_f32_e32 v28, v134, v28
	v_mul_f32_e32 v29, v134, v29
	v_mul_f32_e32 v187, v30, v30
	v_fmac_f32_e32 v187, v31, v31
	v_fmac_f32_e32 v187, v32, v32
	v_fmac_f32_e32 v187, v33, v33
	v_fmac_f32_e32 v187, v26, v26
	v_fmac_f32_e32 v187, v27, v27
	v_fmac_f32_e32 v187, v28, v28
	v_fmac_f32_e32 v187, v29, v29
	v_mul_f32_e32 v86, v135, v86
	v_mul_f32_e32 v87, v135, v87
	v_mul_f32_e32 v88, v135, v88
	v_mul_f32_e32 v89, v135, v89
	v_mul_f32_e32 v82, v135, v82
	v_mul_f32_e32 v83, v135, v83
	v_mul_f32_e32 v84, v135, v84
	v_mul_f32_e32 v85, v135, v85
	v_mul_f32_e32 v188, v86, v86
	v_fmac_f32_e32 v188, v87, v87
	v_fmac_f32_e32 v188, v88, v88
	v_fmac_f32_e32 v188, v89, v89
	v_fmac_f32_e32 v188, v82, v82
	v_fmac_f32_e32 v188, v83, v83
	v_fmac_f32_e32 v188, v84, v84
	v_fmac_f32_e32 v188, v85, v85
	v_mul_f32_e32 v22, v135, v22
	v_mul_f32_e32 v23, v135, v23
	v_mul_f32_e32 v24, v135, v24
	v_mul_f32_e32 v25, v135, v25
	v_mul_f32_e32 v18, v135, v18
	v_mul_f32_e32 v19, v135, v19
	v_mul_f32_e32 v20, v135, v20
	v_mul_f32_e32 v21, v135, v21
	v_mul_f32_e32 v189, v22, v22
	v_fmac_f32_e32 v189, v23, v23
	v_fmac_f32_e32 v189, v24, v24
	v_fmac_f32_e32 v189, v25, v25
	v_fmac_f32_e32 v189, v18, v18
	v_fmac_f32_e32 v189, v19, v19
	v_fmac_f32_e32 v189, v20, v20
	v_fmac_f32_e32 v189, v21, v21
	v_mul_f32_e32 v78, v136, v78
	v_mul_f32_e32 v79, v136, v79
	v_mul_f32_e32 v80, v136, v80
	v_mul_f32_e32 v81, v136, v81
	v_mul_f32_e32 v74, v136, v74
	v_mul_f32_e32 v75, v136, v75
	v_mul_f32_e32 v76, v136, v76
	v_mul_f32_e32 v77, v136, v77
	v_mul_f32_e32 v190, v78, v78
	v_fmac_f32_e32 v190, v79, v79
	v_fmac_f32_e32 v190, v80, v80
	v_fmac_f32_e32 v190, v81, v81
	v_fmac_f32_e32 v190, v74, v74
	v_fmac_f32_e32 v190, v75, v75
	v_fmac_f32_e32 v190, v76, v76
	v_fmac_f32_e32 v190, v77, v77
	v_mul_f32_e32 v14, v136, v14
	v_mul_f32_e32 v15, v136, v15
	v_mul_f32_e32 v16, v136, v16
	v_mul_f32_e32 v17, v136, v17
	v_mul_f32_e32 v10, v136, v10
	v_mul_f32_e32 v11, v136, v11
	v_mul_f32_e32 v12, v136, v12
	v_mul_f32_e32 v13, v136, v13
	v_mul_f32_e32 v191, v14, v14
	v_fmac_f32_e32 v191, v15, v15
	v_fmac_f32_e32 v191, v16, v16
	v_fmac_f32_e32 v191, v17, v17
	v_fmac_f32_e32 v191, v10, v10
	v_fmac_f32_e32 v191, v11, v11
	v_fmac_f32_e32 v191, v12, v12
	v_fmac_f32_e32 v191, v13, v13
	v_mul_f32_e32 v70, v137, v70
	v_mul_f32_e32 v71, v137, v71
	v_mul_f32_e32 v72, v137, v72
	v_mul_f32_e32 v73, v137, v73
	v_mul_f32_e32 v66, v137, v66
	v_mul_f32_e32 v67, v137, v67
	v_mul_f32_e32 v68, v137, v68
	v_mul_f32_e32 v69, v137, v69
	v_mul_f32_e32 v192, v70, v70
	v_fmac_f32_e32 v192, v71, v71
	v_fmac_f32_e32 v192, v72, v72
	v_fmac_f32_e32 v192, v73, v73
	v_fmac_f32_e32 v192, v66, v66
	v_fmac_f32_e32 v192, v67, v67
	v_fmac_f32_e32 v192, v68, v68
	v_fmac_f32_e32 v192, v69, v69
	v_mul_f32_e32 v6, v137, v6
	v_mul_f32_e32 v7, v137, v7
	v_mul_f32_e32 v8, v137, v8
	v_mul_f32_e32 v9, v137, v9
	v_mul_f32_e32 v2, v137, v2
	v_mul_f32_e32 v3, v137, v3
	v_mul_f32_e32 v4, v137, v4
	v_mul_f32_e32 v5, v137, v5
	v_mul_f32_e32 v193, v6, v6
	v_fmac_f32_e32 v193, v7, v7
	v_fmac_f32_e32 v193, v8, v8
	v_fmac_f32_e32 v193, v9, v9
	v_fmac_f32_e32 v193, v2, v2
	v_fmac_f32_e32 v193, v3, v3
	v_fmac_f32_e32 v193, v4, v4
	v_fmac_f32_e32 v193, v5, v5
	ds_bpermute_b32 v194, v164, v178
	ds_bpermute_b32 v195, v164, v179
	ds_bpermute_b32 v196, v164, v180
	ds_bpermute_b32 v197, v164, v181
	ds_bpermute_b32 v198, v164, v182
	ds_bpermute_b32 v199, v164, v183
	ds_bpermute_b32 v200, v164, v184
	ds_bpermute_b32 v201, v164, v185
	s_waitcnt lgkmcnt(0)
	v_add_f32_e32 v178, v178, v194
	v_add_f32_e32 v179, v179, v195
	v_add_f32_e32 v180, v180, v196
	v_add_f32_e32 v181, v181, v197
	v_add_f32_e32 v182, v182, v198
	v_add_f32_e32 v183, v183, v199
	v_add_f32_e32 v184, v184, v200
	v_add_f32_e32 v185, v185, v201
	ds_bpermute_b32 v202, v164, v186
	ds_bpermute_b32 v203, v164, v187
	ds_bpermute_b32 v204, v164, v188
	ds_bpermute_b32 v205, v164, v189
	ds_bpermute_b32 v206, v164, v190
	ds_bpermute_b32 v207, v164, v191
	ds_bpermute_b32 v208, v164, v192
	ds_bpermute_b32 v209, v164, v193
	s_waitcnt lgkmcnt(0)
	v_add_f32_e32 v186, v186, v202
	v_add_f32_e32 v187, v187, v203
	v_add_f32_e32 v188, v188, v204
	v_add_f32_e32 v189, v189, v205
	v_add_f32_e32 v190, v190, v206
	v_add_f32_e32 v191, v191, v207
	v_add_f32_e32 v192, v192, v208
	v_add_f32_e32 v193, v193, v209
	ds_bpermute_b32 v194, v165, v178
	ds_bpermute_b32 v195, v165, v179
	ds_bpermute_b32 v196, v165, v180
	ds_bpermute_b32 v197, v165, v181
	ds_bpermute_b32 v198, v165, v182
	ds_bpermute_b32 v199, v165, v183
	ds_bpermute_b32 v200, v165, v184
	ds_bpermute_b32 v201, v165, v185
	s_waitcnt lgkmcnt(0)
	v_add_f32_e32 v178, v178, v194
	v_add_f32_e32 v179, v179, v195
	v_add_f32_e32 v180, v180, v196
	v_add_f32_e32 v181, v181, v197
	v_add_f32_e32 v182, v182, v198
	v_add_f32_e32 v183, v183, v199
	v_add_f32_e32 v184, v184, v200
	v_add_f32_e32 v185, v185, v201
	ds_bpermute_b32 v202, v165, v186
	ds_bpermute_b32 v203, v165, v187
	ds_bpermute_b32 v204, v165, v188
	ds_bpermute_b32 v205, v165, v189
	ds_bpermute_b32 v206, v165, v190
	ds_bpermute_b32 v207, v165, v191
	ds_bpermute_b32 v208, v165, v192
	ds_bpermute_b32 v209, v165, v193
	s_waitcnt lgkmcnt(0)
	v_add_f32_e32 v186, v186, v202
	v_add_f32_e32 v187, v187, v203
	v_add_f32_e32 v188, v188, v204
	v_add_f32_e32 v189, v189, v205
	v_add_f32_e32 v190, v190, v206
	v_add_f32_e32 v191, v191, v207
	v_add_f32_e32 v192, v192, v208
	v_add_f32_e32 v193, v193, v209
	ds_write_b32 v166, v178 offset:0
	ds_write_b32 v166, v179 offset:16
	ds_write_b32 v166, v180 offset:512
	ds_write_b32 v166, v181 offset:528
	ds_write_b32 v166, v182 offset:1024
	ds_write_b32 v166, v183 offset:1040
	ds_write_b32 v166, v184 offset:1536
	ds_write_b32 v166, v185 offset:1552
	s_waitcnt lgkmcnt(0)
	ds_write_b32 v166, v186 offset:4096
	ds_write_b32 v166, v187 offset:4112
	ds_write_b32 v166, v188 offset:4608
	ds_write_b32 v166, v189 offset:4624
	ds_write_b32 v166, v190 offset:5120
	ds_write_b32 v166, v191 offset:5136
	ds_write_b32 v166, v192 offset:5632
	ds_write_b32 v166, v193 offset:5648
	s_waitcnt lgkmcnt(0)
	s_barrier
; __device__ __forceinline__ u32x4 pack8(const f32x4 a, const f32x4 b) { u32x4 w; w.x = cvt_pk_bf16(a[0], a[1]); w.y = cvt_pk_bf16(a[2], a[3]); w.z = cvt_pk_bf16(b[0], b[1]); w.w = cvt_pk_bf16(b[2], b[3]); return w; }
; __device__ void ph_qknorm(bf16_t* Z, const float* qg, const float* kg, const int WID) {
;     ...
;             ss += __shfl_xor(ss, 1); ss += __shfl_xor(ss, 2); ss += __shfl_xor(ss, 4);
;             const float rstd = rsqrtf(ss * (1.0f / 128.0f) + EPS) * (isk ? 1.0f : 0.08838834764831845f);
;             const f32x4 g0 = isk ? kgv[0] : qgv[0], g1 = isk ? kgv[1] : qgv[1], g2 = isk ? kgv[2] : qgv[2], g3 = isk ? kgv[3] : qgv[3];
;             *(u32x4*)ptr = pack8(a0 * rstd * g0, a1 * rstd * g1); *(u32x4*)(ptr + 8) = pack8(a2 * rstd * g2, a3 * rstd * g3);
	ds_read_b128 v[194:197], v167 offset:0
	ds_read_b128 v[198:201], v167 offset:16
	ds_read_b128 v[202:205], v167 offset:512
	ds_read_b128 v[206:209], v167 offset:528
	s_waitcnt lgkmcnt(0)
	v_add_f32_e32 v194, v194, v195
	v_add_f32_e32 v196, v196, v197
	v_add_f32_e32 v178, v194, v196
	v_add_f32_e32 v198, v198, v199
	v_add_f32_e32 v200, v200, v201
	v_add_f32_e32 v179, v198, v200
	v_add_f32_e32 v202, v202, v203
	v_add_f32_e32 v204, v204, v205
	v_add_f32_e32 v180, v202, v204
	v_add_f32_e32 v206, v206, v207
	v_add_f32_e32 v208, v208, v209
	v_add_f32_e32 v181, v206, v208
	ds_read_b128 v[194:197], v167 offset:1024
	ds_read_b128 v[198:201], v167 offset:1040
	ds_read_b128 v[202:205], v167 offset:1536
	ds_read_b128 v[206:209], v167 offset:1552
	s_waitcnt lgkmcnt(0)
	v_add_f32_e32 v194, v194, v195
	v_add_f32_e32 v196, v196, v197
	v_add_f32_e32 v182, v194, v196
	v_add_f32_e32 v198, v198, v199
	v_add_f32_e32 v200, v200, v201
	v_add_f32_e32 v183, v198, v200
	v_add_f32_e32 v202, v202, v203
	v_add_f32_e32 v204, v204, v205
	v_add_f32_e32 v184, v202, v204
	v_add_f32_e32 v206, v206, v207
	v_add_f32_e32 v208, v208, v209
	v_add_f32_e32 v185, v206, v208
	ds_read_b128 v[194:197], v167 offset:4096
	ds_read_b128 v[198:201], v167 offset:4112
	ds_read_b128 v[202:205], v167 offset:4608
	ds_read_b128 v[206:209], v167 offset:4624
	s_waitcnt lgkmcnt(0)
	v_add_f32_e32 v194, v194, v195
	v_add_f32_e32 v196, v196, v197
	v_add_f32_e32 v186, v194, v196
	v_add_f32_e32 v198, v198, v199
	v_add_f32_e32 v200, v200, v201
	v_add_f32_e32 v187, v198, v200
	v_add_f32_e32 v202, v202, v203
	v_add_f32_e32 v204, v204, v205
	v_add_f32_e32 v188, v202, v204
	v_add_f32_e32 v206, v206, v207
	v_add_f32_e32 v208, v208, v209
	v_add_f32_e32 v189, v206, v208
	ds_read_b128 v[194:197], v167 offset:5120
	ds_read_b128 v[198:201], v167 offset:5136
	ds_read_b128 v[202:205], v167 offset:5632
	ds_read_b128 v[206:209], v167 offset:5648
	s_waitcnt lgkmcnt(0)
	v_add_f32_e32 v194, v194, v195
	v_add_f32_e32 v196, v196, v197
	v_add_f32_e32 v190, v194, v196
	v_add_f32_e32 v198, v198, v199
	v_add_f32_e32 v200, v200, v201
	v_add_f32_e32 v191, v198, v200
	v_add_f32_e32 v202, v202, v203
	v_add_f32_e32 v204, v204, v205
	v_add_f32_e32 v192, v202, v204
	v_add_f32_e32 v206, v206, v207
	v_add_f32_e32 v208, v208, v209
	v_add_f32_e32 v193, v206, v208
	v_fmamk_f32 v178, v178, 0x3c000000, v251
	v_fmamk_f32 v179, v179, 0x3c000000, v251
	v_fmamk_f32 v180, v180, 0x3c000000, v251
	v_fmamk_f32 v181, v181, 0x3c000000, v251
	v_fmamk_f32 v182, v182, 0x3c000000, v251
	v_fmamk_f32 v183, v183, 0x3c000000, v251
	v_fmamk_f32 v184, v184, 0x3c000000, v251
	v_fmamk_f32 v185, v185, 0x3c000000, v251
	v_fmamk_f32 v186, v186, 0x3c000000, v251
	v_fmamk_f32 v187, v187, 0x3c000000, v251
	v_fmamk_f32 v188, v188, 0x3c000000, v251
	v_fmamk_f32 v189, v189, 0x3c000000, v251
	v_fmamk_f32 v190, v190, 0x3c000000, v251
	v_fmamk_f32 v191, v191, 0x3c000000, v251
	v_fmamk_f32 v192, v192, 0x3c000000, v251
	v_fmamk_f32 v193, v193, 0x3c000000, v251
	v_rsq_f32_e32 v178, v178
	v_rsq_f32_e32 v179, v179
	v_rsq_f32_e32 v180, v180
	v_rsq_f32_e32 v181, v181
	v_rsq_f32_e32 v182, v182
	v_rsq_f32_e32 v183, v183
	v_rsq_f32_e32 v184, v184
	v_rsq_f32_e32 v185, v185
	v_rsq_f32_e32 v186, v186
	v_rsq_f32_e32 v187, v187
	v_rsq_f32_e32 v188, v188
	v_rsq_f32_e32 v189, v189
	v_rsq_f32_e32 v190, v190
	v_rsq_f32_e32 v191, v191
	v_rsq_f32_e32 v192, v192
	v_rsq_f32_e32 v193, v193
	s_waitcnt vmcnt(0)
	v_mul_f32_e32 v178, s11, v178
	v_mul_f32_e32 v179, s11, v179
	v_mul_f32_e32 v180, s11, v180
	v_mul_f32_e32 v181, s11, v181
	v_mul_f32_e32 v182, s11, v182
	v_mul_f32_e32 v183, s11, v183
	v_mul_f32_e32 v184, s11, v184
	v_mul_f32_e32 v185, s11, v185
	v_mul_f32_e32 v186, s11, v186
	v_mul_f32_e32 v187, s11, v187
	v_mul_f32_e32 v188, s11, v188
	v_mul_f32_e32 v189, s11, v189
	v_mul_f32_e32 v190, s11, v190
	v_mul_f32_e32 v191, s11, v191
	v_mul_f32_e32 v192, s11, v192
	v_mul_f32_e32 v193, s11, v193
	v_mov_b32_e32 v168, v163
	v_mul_f32_e32 v126, v178, v126
	v_mul_f32_e32 v127, v178, v127
	v_mul_f32_e32 v128, v178, v128
	v_mul_f32_e32 v129, v178, v129
	v_mul_f32_e32 v122, v178, v122
	v_mul_f32_e32 v123, v178, v123
	v_mul_f32_e32 v124, v178, v124
	v_mul_f32_e32 v125, v178, v125
	v_pk_mul_f32 v[126:127], v[126:127], v[138:139]
	v_pk_mul_f32 v[128:129], v[128:129], v[140:141]
	v_pk_mul_f32 v[122:123], v[122:123], v[142:143]
	v_pk_mul_f32 v[124:125], v[124:125], v[144:145]
	v_cvt_pk_bf16_f32 v126, v126, v127
	v_cvt_pk_bf16_f32 v127, v128, v129
	v_cvt_pk_bf16_f32 v128, v122, v123
	v_cvt_pk_bf16_f32 v129, v124, v125
	global_store_dwordx4 v168, v[126:129], s[30:31]
	v_mul_f32_e32 v62, v179, v62
	v_mul_f32_e32 v63, v179, v63
	v_mul_f32_e32 v64, v179, v64
	v_mul_f32_e32 v65, v179, v65
	v_mul_f32_e32 v58, v179, v58
	v_mul_f32_e32 v59, v179, v59
	v_mul_f32_e32 v60, v179, v60
	v_mul_f32_e32 v61, v179, v61
	v_pk_mul_f32 v[62:63], v[62:63], v[138:139]
	v_pk_mul_f32 v[64:65], v[64:65], v[140:141]
	v_pk_mul_f32 v[58:59], v[58:59], v[142:143]
	v_pk_mul_f32 v[60:61], v[60:61], v[144:145]
	v_cvt_pk_bf16_f32 v62, v62, v63
	v_cvt_pk_bf16_f32 v63, v64, v65
	v_cvt_pk_bf16_f32 v64, v58, v59
	v_cvt_pk_bf16_f32 v65, v60, v61
	global_store_dwordx4 v168, v[62:65], s[30:31] offset:256
	v_add_u32_e32 v168, 0x48000, v163
	v_mul_f32_e32 v118, v180, v118
	v_mul_f32_e32 v119, v180, v119
	v_mul_f32_e32 v120, v180, v120
	v_mul_f32_e32 v121, v180, v121
	v_mul_f32_e32 v114, v180, v114
	v_mul_f32_e32 v115, v180, v115
	v_mul_f32_e32 v116, v180, v116
	v_mul_f32_e32 v117, v180, v117
	v_pk_mul_f32 v[118:119], v[118:119], v[138:139]
	v_pk_mul_f32 v[120:121], v[120:121], v[140:141]
	v_pk_mul_f32 v[114:115], v[114:115], v[142:143]
; __device__ __forceinline__ u32x4 pack8(const f32x4 a, const f32x4 b) { u32x4 w; w.x = cvt_pk_bf16(a[0], a[1]); w.y = cvt_pk_bf16(a[2], a[3]); w.z = cvt_pk_bf16(b[0], b[1]); w.w = cvt_pk_bf16(b[2], b[3]); return w; }
; __device__ void ph_qknorm(bf16_t* Z, const float* qg, const float* kg, const int WID) {
;     ...
;             const float rstd = rsqrtf(ss * (1.0f / 128.0f) + EPS) * (isk ? 1.0f : 0.08838834764831845f);
;             const f32x4 g0 = isk ? kgv[0] : qgv[0], g1 = isk ? kgv[1] : qgv[1], g2 = isk ? kgv[2] : qgv[2], g3 = isk ? kgv[3] : qgv[3];
;             *(u32x4*)ptr = pack8(a0 * rstd * g0, a1 * rstd * g1); *(u32x4*)(ptr + 8) = pack8(a2 * rstd * g2, a3 * rstd * g3);
	v_pk_mul_f32 v[116:117], v[116:117], v[144:145]
	v_cvt_pk_bf16_f32 v118, v118, v119
	v_cvt_pk_bf16_f32 v119, v120, v121
	v_cvt_pk_bf16_f32 v120, v114, v115
	v_cvt_pk_bf16_f32 v121, v116, v117
	global_store_dwordx4 v168, v[118:121], s[30:31]
	v_mul_f32_e32 v54, v181, v54
	v_mul_f32_e32 v55, v181, v55
	v_mul_f32_e32 v56, v181, v56
	v_mul_f32_e32 v57, v181, v57
	v_mul_f32_e32 v50, v181, v50
	v_mul_f32_e32 v51, v181, v51
	v_mul_f32_e32 v52, v181, v52
	v_mul_f32_e32 v53, v181, v53
	v_pk_mul_f32 v[54:55], v[54:55], v[138:139]
	v_pk_mul_f32 v[56:57], v[56:57], v[140:141]
	v_pk_mul_f32 v[50:51], v[50:51], v[142:143]
	v_pk_mul_f32 v[52:53], v[52:53], v[144:145]
	v_cvt_pk_bf16_f32 v54, v54, v55
	v_cvt_pk_bf16_f32 v55, v56, v57
	v_cvt_pk_bf16_f32 v56, v50, v51
	v_cvt_pk_bf16_f32 v57, v52, v53
	global_store_dwordx4 v168, v[54:57], s[30:31] offset:256
	v_add_u32_e32 v168, 0x90000, v163
	v_mul_f32_e32 v110, v182, v110
	v_mul_f32_e32 v111, v182, v111
	v_mul_f32_e32 v112, v182, v112
	v_mul_f32_e32 v113, v182, v113
	v_mul_f32_e32 v106, v182, v106
	v_mul_f32_e32 v107, v182, v107
	v_mul_f32_e32 v108, v182, v108
	v_mul_f32_e32 v109, v182, v109
	v_pk_mul_f32 v[110:111], v[110:111], v[138:139]
	v_pk_mul_f32 v[112:113], v[112:113], v[140:141]
	v_pk_mul_f32 v[106:107], v[106:107], v[142:143]
	v_pk_mul_f32 v[108:109], v[108:109], v[144:145]
	v_cvt_pk_bf16_f32 v110, v110, v111
	v_cvt_pk_bf16_f32 v111, v112, v113
	v_cvt_pk_bf16_f32 v112, v106, v107
	v_cvt_pk_bf16_f32 v113, v108, v109
	global_store_dwordx4 v168, v[110:113], s[30:31]
	v_mul_f32_e32 v46, v183, v46
	v_mul_f32_e32 v47, v183, v47
	v_mul_f32_e32 v48, v183, v48
	v_mul_f32_e32 v49, v183, v49
	v_mul_f32_e32 v42, v183, v42
	v_mul_f32_e32 v43, v183, v43
	v_mul_f32_e32 v44, v183, v44
	v_mul_f32_e32 v45, v183, v45
	v_pk_mul_f32 v[46:47], v[46:47], v[138:139]
	v_pk_mul_f32 v[48:49], v[48:49], v[140:141]
	v_pk_mul_f32 v[42:43], v[42:43], v[142:143]
	v_pk_mul_f32 v[44:45], v[44:45], v[144:145]
	v_cvt_pk_bf16_f32 v46, v46, v47
	v_cvt_pk_bf16_f32 v47, v48, v49
	v_cvt_pk_bf16_f32 v48, v42, v43
	v_cvt_pk_bf16_f32 v49, v44, v45
	global_store_dwordx4 v168, v[46:49], s[30:31] offset:256
	v_add_u32_e32 v168, 0xd8000, v163
	v_mul_f32_e32 v102, v184, v102
	v_mul_f32_e32 v103, v184, v103
	v_mul_f32_e32 v104, v184, v104
	v_mul_f32_e32 v105, v184, v105
	v_mul_f32_e32 v98, v184, v98
	v_mul_f32_e32 v99, v184, v99
	v_mul_f32_e32 v100, v184, v100
	v_mul_f32_e32 v101, v184, v101
	v_pk_mul_f32 v[102:103], v[102:103], v[138:139]
	v_pk_mul_f32 v[104:105], v[104:105], v[140:141]
	v_pk_mul_f32 v[98:99], v[98:99], v[142:143]
	v_pk_mul_f32 v[100:101], v[100:101], v[144:145]
	v_cvt_pk_bf16_f32 v102, v102, v103
	v_cvt_pk_bf16_f32 v103, v104, v105
	v_cvt_pk_bf16_f32 v104, v98, v99
	v_cvt_pk_bf16_f32 v105, v100, v101
	global_store_dwordx4 v168, v[102:105], s[30:31]
	v_mul_f32_e32 v38, v185, v38
	v_mul_f32_e32 v39, v185, v39
	v_mul_f32_e32 v40, v185, v40
	v_mul_f32_e32 v41, v185, v41
	v_mul_f32_e32 v34, v185, v34
	v_mul_f32_e32 v35, v185, v35
	v_mul_f32_e32 v36, v185, v36
	v_mul_f32_e32 v37, v185, v37
	v_pk_mul_f32 v[38:39], v[38:39], v[138:139]
	v_pk_mul_f32 v[40:41], v[40:41], v[140:141]
	v_pk_mul_f32 v[34:35], v[34:35], v[142:143]
	v_pk_mul_f32 v[36:37], v[36:37], v[144:145]
	v_cvt_pk_bf16_f32 v38, v38, v39
	v_cvt_pk_bf16_f32 v39, v40, v41
	v_cvt_pk_bf16_f32 v40, v34, v35
	v_cvt_pk_bf16_f32 v41, v36, v37
	global_store_dwordx4 v168, v[38:41], s[30:31] offset:256
	v_add_u32_e32 v168, 0x240000, v163
	v_mul_f32_e32 v94, v186, v94
	v_mul_f32_e32 v95, v186, v95
	v_mul_f32_e32 v96, v186, v96
	v_mul_f32_e32 v97, v186, v97
	v_mul_f32_e32 v90, v186, v90
	v_mul_f32_e32 v91, v186, v91
	v_mul_f32_e32 v92, v186, v92
	v_mul_f32_e32 v93, v186, v93
	v_pk_mul_f32 v[94:95], v[94:95], v[138:139]
	v_pk_mul_f32 v[96:97], v[96:97], v[140:141]
	v_pk_mul_f32 v[90:91], v[90:91], v[142:143]
	v_pk_mul_f32 v[92:93], v[92:93], v[144:145]
	v_cvt_pk_bf16_f32 v94, v94, v95
	v_cvt_pk_bf16_f32 v95, v96, v97
	v_cvt_pk_bf16_f32 v96, v90, v91
	v_cvt_pk_bf16_f32 v97, v92, v93
	global_store_dwordx4 v168, v[94:97], s[30:31]
	v_mul_f32_e32 v30, v187, v30
	v_mul_f32_e32 v31, v187, v31
	v_mul_f32_e32 v32, v187, v32
	v_mul_f32_e32 v33, v187, v33
; __device__ __forceinline__ u32x4 pack8(const f32x4 a, const f32x4 b) { u32x4 w; w.x = cvt_pk_bf16(a[0], a[1]); w.y = cvt_pk_bf16(a[2], a[3]); w.z = cvt_pk_bf16(b[0], b[1]); w.w = cvt_pk_bf16(b[2], b[3]); return w; }
; __device__ void ph_qknorm(bf16_t* Z, const float* qg, const float* kg, const int WID) {
;     ...
;             const float rstd = rsqrtf(ss * (1.0f / 128.0f) + EPS) * (isk ? 1.0f : 0.08838834764831845f);
;             const f32x4 g0 = isk ? kgv[0] : qgv[0], g1 = isk ? kgv[1] : qgv[1], g2 = isk ? kgv[2] : qgv[2], g3 = isk ? kgv[3] : qgv[3];
;             *(u32x4*)ptr = pack8(a0 * rstd * g0, a1 * rstd * g1); *(u32x4*)(ptr + 8) = pack8(a2 * rstd * g2, a3 * rstd * g3);
	v_mul_f32_e32 v26, v187, v26
	v_mul_f32_e32 v27, v187, v27
	v_mul_f32_e32 v28, v187, v28
	v_mul_f32_e32 v29, v187, v29
	v_pk_mul_f32 v[30:31], v[30:31], v[138:139]
	v_pk_mul_f32 v[32:33], v[32:33], v[140:141]
	v_pk_mul_f32 v[26:27], v[26:27], v[142:143]
	v_pk_mul_f32 v[28:29], v[28:29], v[144:145]
	v_cvt_pk_bf16_f32 v30, v30, v31
	v_cvt_pk_bf16_f32 v31, v32, v33
	v_cvt_pk_bf16_f32 v32, v26, v27
	v_cvt_pk_bf16_f32 v33, v28, v29
	global_store_dwordx4 v168, v[30:33], s[30:31] offset:256
	v_add_u32_e32 v168, 0x288000, v163
	v_mul_f32_e32 v86, v188, v86
	v_mul_f32_e32 v87, v188, v87
	v_mul_f32_e32 v88, v188, v88
	v_mul_f32_e32 v89, v188, v89
	v_mul_f32_e32 v82, v188, v82
	v_mul_f32_e32 v83, v188, v83
	v_mul_f32_e32 v84, v188, v84
	v_mul_f32_e32 v85, v188, v85
	v_pk_mul_f32 v[86:87], v[86:87], v[138:139]
	v_pk_mul_f32 v[88:89], v[88:89], v[140:141]
	v_pk_mul_f32 v[82:83], v[82:83], v[142:143]
	v_pk_mul_f32 v[84:85], v[84:85], v[144:145]
	v_cvt_pk_bf16_f32 v86, v86, v87
	v_cvt_pk_bf16_f32 v87, v88, v89
	v_cvt_pk_bf16_f32 v88, v82, v83
	v_cvt_pk_bf16_f32 v89, v84, v85
	global_store_dwordx4 v168, v[86:89], s[30:31]
	v_mul_f32_e32 v22, v189, v22
	v_mul_f32_e32 v23, v189, v23
	v_mul_f32_e32 v24, v189, v24
	v_mul_f32_e32 v25, v189, v25
	v_mul_f32_e32 v18, v189, v18
	v_mul_f32_e32 v19, v189, v19
	v_mul_f32_e32 v20, v189, v20
	v_mul_f32_e32 v21, v189, v21
	v_pk_mul_f32 v[22:23], v[22:23], v[138:139]
	v_pk_mul_f32 v[24:25], v[24:25], v[140:141]
	v_pk_mul_f32 v[18:19], v[18:19], v[142:143]
	v_pk_mul_f32 v[20:21], v[20:21], v[144:145]
	v_cvt_pk_bf16_f32 v22, v22, v23
	v_cvt_pk_bf16_f32 v23, v24, v25
	v_cvt_pk_bf16_f32 v24, v18, v19
	v_cvt_pk_bf16_f32 v25, v20, v21
	global_store_dwordx4 v168, v[22:25], s[30:31] offset:256
	v_add_u32_e32 v168, 0x2d0000, v163
	v_mul_f32_e32 v78, v190, v78
	v_mul_f32_e32 v79, v190, v79
	v_mul_f32_e32 v80, v190, v80
	v_mul_f32_e32 v81, v190, v81
	v_mul_f32_e32 v74, v190, v74
	v_mul_f32_e32 v75, v190, v75
	v_mul_f32_e32 v76, v190, v76
	v_mul_f32_e32 v77, v190, v77
	v_pk_mul_f32 v[78:79], v[78:79], v[138:139]
	v_pk_mul_f32 v[80:81], v[80:81], v[140:141]
	v_pk_mul_f32 v[74:75], v[74:75], v[142:143]
	v_pk_mul_f32 v[76:77], v[76:77], v[144:145]
	v_cvt_pk_bf16_f32 v78, v78, v79
	v_cvt_pk_bf16_f32 v79, v80, v81
	v_cvt_pk_bf16_f32 v80, v74, v75
	v_cvt_pk_bf16_f32 v81, v76, v77
	global_store_dwordx4 v168, v[78:81], s[30:31]
	v_mul_f32_e32 v14, v191, v14
	v_mul_f32_e32 v15, v191, v15
	v_mul_f32_e32 v16, v191, v16
	v_mul_f32_e32 v17, v191, v17
	v_mul_f32_e32 v10, v191, v10
	v_mul_f32_e32 v11, v191, v11
	v_mul_f32_e32 v12, v191, v12
	v_mul_f32_e32 v13, v191, v13
	v_pk_mul_f32 v[14:15], v[14:15], v[138:139]
	v_pk_mul_f32 v[16:17], v[16:17], v[140:141]
	v_pk_mul_f32 v[10:11], v[10:11], v[142:143]
	v_pk_mul_f32 v[12:13], v[12:13], v[144:145]
	v_cvt_pk_bf16_f32 v14, v14, v15
	v_cvt_pk_bf16_f32 v15, v16, v17
	v_cvt_pk_bf16_f32 v16, v10, v11
	v_cvt_pk_bf16_f32 v17, v12, v13
	global_store_dwordx4 v168, v[14:17], s[30:31] offset:256
	v_add_u32_e32 v168, 0x318000, v163
	v_mul_f32_e32 v70, v192, v70
	v_mul_f32_e32 v71, v192, v71
	v_mul_f32_e32 v72, v192, v72
	v_mul_f32_e32 v73, v192, v73
	v_mul_f32_e32 v66, v192, v66
	v_mul_f32_e32 v67, v192, v67
	v_mul_f32_e32 v68, v192, v68
	v_mul_f32_e32 v69, v192, v69
	v_pk_mul_f32 v[70:71], v[70:71], v[138:139]
	v_pk_mul_f32 v[72:73], v[72:73], v[140:141]
	v_pk_mul_f32 v[66:67], v[66:67], v[142:143]
	v_pk_mul_f32 v[68:69], v[68:69], v[144:145]
	v_cvt_pk_bf16_f32 v70, v70, v71
	v_cvt_pk_bf16_f32 v71, v72, v73
	v_cvt_pk_bf16_f32 v72, v66, v67
	v_cvt_pk_bf16_f32 v73, v68, v69
	global_store_dwordx4 v168, v[70:73], s[30:31]
	v_mul_f32_e32 v6, v193, v6
	v_mul_f32_e32 v7, v193, v7
	v_mul_f32_e32 v8, v193, v8
	v_mul_f32_e32 v9, v193, v9
	v_mul_f32_e32 v2, v193, v2
	v_mul_f32_e32 v3, v193, v3
	v_mul_f32_e32 v4, v193, v4
	v_mul_f32_e32 v5, v193, v5
	v_pk_mul_f32 v[6:7], v[6:7], v[138:139]
	v_pk_mul_f32 v[8:9], v[8:9], v[140:141]
	v_pk_mul_f32 v[2:3], v[2:3], v[142:143]
	v_pk_mul_f32 v[4:5], v[4:5], v[144:145]
	v_cvt_pk_bf16_f32 v6, v6, v7
	v_cvt_pk_bf16_f32 v7, v8, v9
	v_cvt_pk_bf16_f32 v8, v2, v3
	v_cvt_pk_bf16_f32 v9, v4, v5
	global_store_dwordx4 v168, v[6:9], s[30:31] offset:256
	s_branch .LBB0_1033
